# placement pad +8 bytes after fox prologue
# baseline (speedup 1.0000x reference)
; #define GAS __attribute__((address_space(1)))
; template <int MODE> ...
;     ...
;     u32x4 kreg = *(const GAS u32x4*)(kg + (size_t)t_first * 64 * LDH), vreg = *(const GAS u32x4*)(vg + (size_t)t_first * 64 * LDH);
;     float cq = 0.f;
;     if (MODE == 0) {
;         float lf[4];
; #pragma unroll
;         for (int i = 0; i < 4; ++i) { const float x = FL[(rowbase + 4 * tid + i) * 8] + bfv; lf[i] = (fminf(x, 0.f) - __logf(1.f + __expf(-fabsf(x)))) * L2E; }
;         const float s1 = lf[0], s2 = s1 + lf[1], s3 = s2 + lf[2], s4 = s3 + lf[3];
;         float v = s4;
; #pragma unroll
;         for (int off = 1; off < 64; off <<= 1) { const float n = __shfl_up(v, off); if (lane >= off) v += n; }
;         if (lane == 63) wt[wid] = v;
;         __syncthreads();
.LBB0_811:
	v_readlane_b32 s2, v254, 8
	s_mul_i32 s0, s2, 0x2aab
	s_lshr_b32 s1, s0, 31
	s_lshr_b32 s0, s0, 16
	s_add_i32 s0, s0, s1
	s_mul_i32 s1, s0, 6
	s_sub_i32 s4, s2, s1
	s_sext_i32_i16 s1, s4
	s_bfe_i64 s[4:5], s[4:5], 0x100000
	s_lshl_b32 s2, s1, 6
	s_lshl_b64 s[4:5], s[4:5], 2
	v_readlane_b32 s1, v252, 58
	s_add_u32 s8, s1, s4
	v_readlane_b32 s1, v252, 59
	s_addc_u32 s9, s1, s5
	s_add_u32 s4, s23, s4
	v_readlane_b32 s1, v252, 55
	s_addc_u32 s5, s1, s5
	v_mov_b32_e32 v1, v230
	global_load_dword v19, v0, s[4:5]
	s_ashr_i32 s3, s2, 31
	v_readfirstlane_b32 s1, v1
	s_ashr_i32 s6, s1, 6
	s_bfe_i64 s[0:1], s[0:1], 0x100000
	s_lshl_b64 s[4:5], s[0:1], 11
	v_readlane_b32 s0, v252, 56
	v_ashrrev_i32_e32 v18, 3, v1
	v_readlane_b32 s1, v252, 57
	v_add_u32_e32 v4, s4, v18
	v_lshlrev_b32_e32 v12, 2, v1
	v_mov_b64_e32 v[2:3], s[0:1]
	s_movk_i32 s0, 0x1880
	v_mad_i64_i32 v[2:3], s[0:1], v4, s0, v[2:3]
	v_lshlrev_b32_e32 v4, 3, v1
	v_ashrrev_i32_e32 v13, 31, v12
	v_and_b32_e32 v4, 56, v4
	v_lshl_add_u64 v[14:15], s[4:5], 0, v[12:13]
	v_lshl_add_u64 v[2:3], s[2:3], 1, v[2:3]
	v_lshlrev_b32_e32 v10, 1, v4
	v_mov_b32_e32 v11, v0
	v_lshlrev_b64 v[14:15], 5, v[14:15]
	v_lshl_add_u64 v[98:99], v[2:3], 0, v[10:11]
	v_lshl_add_u64 v[16:17], s[8:9], 0, v[14:15]
	global_load_dwordx4 v[2:5], v[98:99], off offset:768
	global_load_dwordx4 v[6:9], v[98:99], off offset:1536
	global_load_dword v11, v[16:17], off
	global_load_dword v176, v[16:17], off offset:32
	global_load_dword v177, v[16:17], off offset:64
	global_load_dword v179, v[16:17], off offset:96
	s_mov_b32 s8, 0xbfb8aa3b
	s_mov_b32 s7, 0x800000
	s_mov_b32 s9, 0x3f317217
	s_mov_b32 s10, 0x7f800000
	v_mov_b32_e32 v21, 0x41b17218
	s_waitcnt vmcnt(0)
	v_add_f32_e32 v11, v19, v11
	v_min_f32_e32 v13, 0, v11
	v_mul_f32_e64 v11, |v11|, s8
	v_exp_f32_e32 v11, v11
	s_nop 0
	v_add_f32_e32 v11, 1.0, v11
	v_cmp_gt_f32_e32 vcc, s7, v11
	s_nop 1
	v_cndmask_b32_e64 v14, 0, 32, vcc
	v_ldexp_f32 v11, v11, v14
	v_log_f32_e32 v11, v11
	s_nop 0
	v_mul_f32_e32 v14, 0x3f317217, v11
	v_fma_f32 v14, v11, s9, -v14
	v_fmac_f32_e32 v14, 0x3377d1cf, v11
	v_fmac_f32_e32 v14, 0x3f317217, v11
	v_cmp_lt_f32_e64 s[0:1], |v11|, s10
	s_nop 1
	v_cndmask_b32_e64 v11, v11, v14, s[0:1]
	v_cndmask_b32_e32 v14, 0, v21, vcc
	v_sub_f32_e32 v11, v11, v14
	v_sub_f32_e32 v11, v13, v11
	v_mul_f32_e32 v14, 0x3fb8aa3b, v11
	v_add_f32_e32 v11, v19, v176
	v_min_f32_e32 v13, 0, v11
	v_mul_f32_e64 v11, |v11|, s8
	v_exp_f32_e32 v11, v11
	s_nop 0
	v_add_f32_e32 v11, 1.0, v11
	v_cmp_gt_f32_e32 vcc, s7, v11
	s_nop 1
	v_cndmask_b32_e64 v15, 0, 32, vcc
	v_ldexp_f32 v11, v11, v15
	v_log_f32_e32 v11, v11
	s_nop 0
	v_mul_f32_e32 v15, 0x3f317217, v11
	v_fma_f32 v15, v11, s9, -v15
	v_fmac_f32_e32 v15, 0x3377d1cf, v11
	v_fmac_f32_e32 v15, 0x3f317217, v11
	v_cmp_lt_f32_e64 s[0:1], |v11|, s10
	s_nop 1
	v_cndmask_b32_e64 v11, v11, v15, s[0:1]
	v_cndmask_b32_e32 v15, 0, v21, vcc
	v_sub_f32_e32 v11, v11, v15
	v_sub_f32_e32 v13, v13, v11
	v_add_f32_e32 v11, v19, v177
	v_min_f32_e32 v15, 0, v11
	v_mul_f32_e64 v11, |v11|, s8
	v_exp_f32_e32 v11, v11
	s_nop 0
	v_add_f32_e32 v11, 1.0, v11
	v_cmp_gt_f32_e32 vcc, s7, v11
	s_nop 1
	v_cndmask_b32_e64 v20, 0, 32, vcc
	v_ldexp_f32 v11, v11, v20
	v_log_f32_e32 v11, v11
	s_nop 0
	v_mul_f32_e32 v20, 0x3f317217, v11
	v_fma_f32 v20, v11, s9, -v20
	v_fmac_f32_e32 v20, 0x3377d1cf, v11
	v_fmac_f32_e32 v20, 0x3f317217, v11
	v_cmp_lt_f32_e64 s[0:1], |v11|, s10
	s_nop 1
	v_cndmask_b32_e64 v11, v11, v20, s[0:1]
	v_cndmask_b32_e32 v20, 0, v21, vcc
	v_sub_f32_e32 v11, v11, v20
	v_sub_f32_e32 v20, v15, v11
	v_add_f32_e32 v11, v19, v179
	s_nop 0
	s_nop 0
	s_nop 0
	s_nop 0
	s_nop 0
	v_min_f32_e32 v15, 0, v11
	v_mul_f32_e64 v11, |v11|, s8
	v_exp_f32_e32 v11, v11
	v_add_u32_e32 v19, -1, v224
	v_add_f32_e32 v11, 1.0, v11
	v_cmp_gt_f32_e32 vcc, s7, v11
	s_nop 1
	v_cndmask_b32_e64 v16, 0, 32, vcc
	v_ldexp_f32 v11, v11, v16
	v_log_f32_e32 v11, v11
	s_nop 0
	v_mul_f32_e32 v16, 0x3f317217, v11
	v_fma_f32 v16, v11, s9, -v16
	v_fmac_f32_e32 v16, 0x3377d1cf, v11
	v_fmac_f32_e32 v16, 0x3f317217, v11
	v_cmp_lt_f32_e64 s[0:1], |v11|, s10
	s_nop 1
	v_cndmask_b32_e64 v11, v11, v16, s[0:1]
	v_cndmask_b32_e32 v16, 0, v21, vcc
	v_sub_f32_e32 v11, v11, v16
	v_sub_f32_e32 v17, v15, v11
	v_fmamk_f32 v15, v13, 0x3fb8aa3b, v14
	v_and_b32_e32 v13, 64, v224
	v_cmp_lt_i32_e32 vcc, v19, v13
	v_fmamk_f32 v16, v20, 0x3fb8aa3b, v15
	v_fmamk_f32 v17, v17, 0x3fb8aa3b, v16
	v_cndmask_b32_e32 v19, v19, v224, vcc
	v_lshlrev_b32_e32 v19, 2, v19
	ds_bpermute_b32 v19, v19, v17
	v_and_b32_e32 v11, 63, v1
	v_cmp_eq_u32_e32 vcc, 0, v11
	v_add_u32_e32 v20, -2, v224
	s_waitcnt lgkmcnt(0)
	v_add_f32_e32 v19, v17, v19
	v_cndmask_b32_e32 v19, v19, v17, vcc
	v_cmp_lt_i32_e32 vcc, v20, v13
	s_nop 1
	v_cndmask_b32_e32 v20, v20, v224, vcc
	v_lshlrev_b32_e32 v20, 2, v20
	ds_bpermute_b32 v20, v20, v19
	v_cmp_gt_u32_e32 vcc, 2, v11
	s_waitcnt lgkmcnt(0)
	v_add_f32_e32 v20, v19, v20
	v_cndmask_b32_e32 v19, v20, v19, vcc
	v_add_u32_e32 v20, -4, v224
	v_cmp_lt_i32_e32 vcc, v20, v13
	s_nop 1
	v_cndmask_b32_e32 v20, v20, v224, vcc
	v_lshlrev_b32_e32 v20, 2, v20
	ds_bpermute_b32 v20, v20, v19
	v_cmp_gt_u32_e32 vcc, 4, v11
	s_waitcnt lgkmcnt(0)
	v_add_f32_e32 v20, v19, v20
	v_cndmask_b32_e32 v19, v20, v19, vcc
	v_add_u32_e32 v20, -8, v224
	v_cmp_lt_i32_e32 vcc, v20, v13
	s_nop 1
	v_cndmask_b32_e32 v20, v20, v224, vcc
	v_lshlrev_b32_e32 v20, 2, v20
	ds_bpermute_b32 v20, v20, v19
	v_cmp_gt_u32_e32 vcc, 8, v11
	s_waitcnt lgkmcnt(0)
	v_add_f32_e32 v20, v19, v20
	v_cndmask_b32_e32 v19, v20, v19, vcc
	v_add_u32_e32 v20, -16, v224
	v_cmp_lt_i32_e32 vcc, v20, v13
	s_nop 1
	v_cndmask_b32_e32 v20, v20, v224, vcc
	v_lshlrev_b32_e32 v20, 2, v20
	ds_bpermute_b32 v20, v20, v19
	v_cmp_gt_u32_e32 vcc, 16, v11
	s_waitcnt lgkmcnt(0)
	v_add_f32_e32 v20, v19, v20
	v_cndmask_b32_e32 v19, v20, v19, vcc
	v_subrev_u32_e32 v20, 32, v224
	v_cmp_lt_i32_e32 vcc, v20, v13
	s_nop 1
	v_cndmask_b32_e32 v20, v20, v224, vcc
	v_lshlrev_b32_e32 v20, 2, v20
	ds_bpermute_b32 v20, v20, v19
	v_cmp_eq_u32_e32 vcc, 63, v11
	s_waitcnt lgkmcnt(0)
	v_add_f32_e32 v20, v19, v20
	s_and_saveexec_b64 s[0:1], vcc
	s_lshl_b32 s7, s6, 2
	s_add_i32 s7, s7, 0
	v_mov_b32_e32 v21, s7
	ds_write_b32 v21, v20 offset:45056
	s_or_b64 exec, exec, s[0:1]
	s_cmp_lt_i32 s6, 1
	s_waitcnt lgkmcnt(0)
	s_barrier
	s_cbranch_scc1 .LBB0_860
	ds_read_b32 v21, v0 offset:45056
	s_waitcnt lgkmcnt(0)
	v_add_f32_e32 v21, 0, v21
	s_cmp_lt_i32 s6, 2
	s_cbranch_scc1 .LBB0_816
